# attention loop: K fragments 0-7 issued at loop head with counted lgkmcnt waits; cross-half row-max swap and canonicalizing max moved to the rare rescale path
# speedup vs baseline: 1.0069x; 1.0069x over previous
; template <int KB, bool HASY>
; __device__ __forceinline__ void phaseA(f32x16& X0, f32x16& X1, f32x16& Y0, f32x16& Y1, bf16x8& pa0, bf16x8& pa1, bf16x8& pa2, bf16x8& pa3,
;                                        const bf16x8* qr, const f32x16& negm, int kaddr, VFr& vf, int vb, float& l_reg) {
;   SBAR();
;   float ls = 0.f;
;   bf16x8 k0 = rd128<KOFF(KB, 0, 0)>(kaddr), k1 = rd128<KOFF(KB, 1, 0)>(kaddr), k2 = rd128<KOFF(KB, 0, 1)>(kaddr), k3 = rd128<KOFF(KB, 1, 1)>(kaddr);
;   if (HASY) { EXP4(Y0, 0); EXP4(Y0, 4); }
;   SBAR(); WAIT4(k0, k1, k2, k3);
;   bf16x8 k4 = rd128<KOFF(KB, 0, 2)>(kaddr), k5 = rd128<KOFF(KB, 1, 2)>(kaddr), k6 = rd128<KOFF(KB, 0, 3)>(kaddr), k7 = rd128<KOFF(KB, 1, 3)>(kaddr);
;   SBAR();
;   X0 = MF(k0, qr[0], negm); if (HASY) { EXP4(Y0, 8); SUM4(Y0, 0); } SBAR();
;   X1 = MF(k1, qr[0], negm); if (HASY) { EXP4(Y0, 12); SUM4(Y0, 4); } SBAR();
;   X0 = MF(k2, qr[1], X0); if (HASY) { PACK8(Y0, 0, pa0); } SBAR();
;   X1 = MF(k3, qr[1], X1); if (HASY) { EXP4(Y1, 0); SUM4(Y0, 8); } SBAR();
;   WAIT4(k4, k5, k6, k7);
;   bf16x8 k8 = rd128<KOFF(KB, 0, 4)>(kaddr), k9 = rd128<KOFF(KB, 1, 4)>(kaddr), k10 = rd128<KOFF(KB, 0, 5)>(kaddr), k11 = rd128<KOFF(KB, 1, 5)>(kaddr);
;   SBAR();
;   X0 = MF(k4, qr[2], X0); if (HASY) { EXP4(Y1, 4); SUM4(Y0, 12); } SBAR();
;   X1 = MF(k5, qr[2], X1); if (HASY) { PACK8(Y0, 8, pa1); } SBAR();
;   X0 = MF(k6, qr[3], X0); if (HASY) { EXP4(Y1, 8); SUM4(Y1, 0); } SBAR();
;   X1 = MF(k7, qr[3], X1); if (HASY) { EXP4(Y1, 12); SUM4(Y1, 4); } SBAR();
;   WAIT4(k8, k9, k10, k11);
;   SBAR();
;   X0 = MF(k8, qr[4], X0); if (HASY) { PACK8(Y1, 0, pa2); } SBAR();
;   X1 = MF(k9, qr[4], X1); if (HASY) { SUM4(Y1, 8); SUM4(Y1, 12); } SBAR();
;   X0 = MF(k10, qr[5], X0); if (HASY) { PACK8(Y1, 8, pa3); } SBAR();
;   X1 = MF(k11, qr[5], X1); if (HASY) vfr_issue<0>(vf, vb);
;   l_reg += ls;
;   SBAR();
; }
; template <bool HASX>
; __device__ __forceinline__ float phaseB(f32x16* o, bf16x8 pa0, bf16x8 pa1, bf16x8 pa2, bf16x8 pa3, VFr& f, int vb, const f32x16& X0, const f32x16& X1) {
;   SBAR(); VWAIT(f); VFr g; vfr_issue<2>(g, vb); SBAR();
;   float a = 0.f, b = 0.f;
;   o[0] = MF(pa0, PKV(f.a0, f.b0), o[0]); SBAR(); o[1] = MF(pa0, PKV(f.c0, f.d0), o[1]);
;   if (HASX) { a = MX3(X0[0], X0[1], X1[0]); b = MX3(X0[2], X0[3], X1[1]); a = MX3(a, X1[2], X1[3]); b = MX3(b, X0[4], X0[5]); } SBAR();
.LBB0_249:
	s_mov_b32 s76, s53
	s_mov_b32 s53, s18
	v_add_u32_e32 v0, s53, v192
	ds_read_b128 v[34:37], v184 offset:0x3400
	ds_read_b128 v[38:41], v184 offset:0x4e00
	ds_read_b128 v[42:45], v184 offset:0x3420
	ds_read_b128 v[46:49], v184 offset:0x4e20
	ds_read_b128 v[170:173], v184 offset:0x3440
	ds_read_b128 v[174:177], v184 offset:0x4e40
	ds_read_b128 v[204:207], v184 offset:0x3460
	ds_read_b128 v[208:211], v184 offset:0x4e60
	v_exp_f32_e32 v82, v82
	v_exp_f32_e32 v195, v83
	v_exp_f32_e32 v84, v84
	v_exp_f32_e32 v196, v85
	v_exp_f32_e32 v83, v86
	v_exp_f32_e32 v85, v87
	v_exp_f32_e32 v86, v88
	v_exp_f32_e32 v87, v89
	s_waitcnt lgkmcnt(7)
	v_mfma_f32_32x32x16_bf16 v[114:129], v[34:37], v[150:153], v[50:65]
	v_exp_f32_e32 v88, v90
	v_exp_f32_e32 v89, v91
	v_exp_f32_e32 v90, v92
	v_exp_f32_e32 v91, v93
	s_waitcnt lgkmcnt(6)
	v_mfma_f32_32x32x16_bf16 v[98:113], v[38:41], v[150:153], v[50:65]
	v_exp_f32_e32 v92, v94
	v_exp_f32_e32 v93, v95
	v_exp_f32_e32 v94, v96
	v_exp_f32_e32 v95, v97
	s_waitcnt lgkmcnt(5)
	v_mfma_f32_32x32x16_bf16 v[114:129], v[42:45], v[146:149], v[114:129]
	v_cvt_pk_bf16_f32 v34, v82, v195
	v_cvt_pk_bf16_f32 v35, v84, v196
	v_cvt_pk_bf16_f32 v36, v83, v85
	v_cvt_pk_bf16_f32 v37, v86, v87
	s_waitcnt lgkmcnt(4)
	v_mfma_f32_32x32x16_bf16 v[98:113], v[46:49], v[146:149], v[98:113]
	v_exp_f32_e32 v96, v66
	v_exp_f32_e32 v97, v67
	v_exp_f32_e32 v197, v68
	v_exp_f32_e32 v198, v69
	ds_read_b128 v[38:41], v184 offset:0x3480
	ds_read_b128 v[66:69], v184 offset:0x4e80
	ds_read_b128 v[212:215], v184 offset:0x34a0
	ds_read_b128 v[216:219], v184 offset:0x4ea0
	s_waitcnt lgkmcnt(4)
	v_mfma_f32_32x32x16_bf16 v[114:129], v[170:173], v[142:145], v[114:129]
	v_exp_f32_e32 v199, v70
	v_exp_f32_e32 v200, v71
	v_exp_f32_e32 v201, v72
	v_exp_f32_e32 v202, v73
	v_mfma_f32_32x32x16_bf16 v[98:113], v[174:177], v[142:145], v[98:113]
	v_cvt_pk_bf16_f32 v42, v88, v89
	v_cvt_pk_bf16_f32 v43, v90, v91
	v_cvt_pk_bf16_f32 v44, v92, v93
	v_cvt_pk_bf16_f32 v45, v94, v95
	v_mfma_f32_32x32x16_bf16 v[114:129], v[204:207], v[138:141], v[114:129]
	v_exp_f32_e32 v203, v74
	v_exp_f32_e32 v204, v75
	v_exp_f32_e32 v205, v76
	v_exp_f32_e32 v206, v77
	v_mfma_f32_32x32x16_bf16 v[98:113], v[208:211], v[138:141], v[98:113]
	v_exp_f32_e32 v207, v78
	v_exp_f32_e32 v208, v79
	v_exp_f32_e32 v209, v80
	v_exp_f32_e32 v210, v81
	s_waitcnt lgkmcnt(0)
	s_nop 0
	v_mfma_f32_32x32x16_bf16 v[114:129], v[38:41], v[134:137], v[114:129]
	v_cvt_pk_bf16_f32 v46, v96, v97
	v_cvt_pk_bf16_f32 v47, v197, v198
	v_cvt_pk_bf16_f32 v48, v199, v200
	v_cvt_pk_bf16_f32 v49, v201, v202
	v_mfma_f32_32x32x16_bf16 v[98:113], v[66:69], v[134:137], v[98:113]
	v_mfma_f32_32x32x16_bf16 v[114:129], v[212:215], v[130:133], v[114:129]
	v_cvt_pk_bf16_f32 v38, v203, v204
	v_cvt_pk_bf16_f32 v39, v205, v206
	v_cvt_pk_bf16_f32 v40, v207, v208
	v_cvt_pk_bf16_f32 v41, v209, v210
	ds_read_b64_tr_b16 v[78:79], v0 offset:0
	ds_read_b64_tr_b16 v[80:81], v0 offset:0x400
	ds_read_b64_tr_b16 v[74:75], v0 offset:0x200
	v_mfma_f32_32x32x16_bf16 v[98:113], v[216:219], v[130:133], v[98:113]
	ds_read_b64_tr_b16 v[76:77], v0 offset:0x600
	ds_read_b64_tr_b16 v[70:71], v0 offset:0x800
	ds_read_b64_tr_b16 v[72:73], v0 offset:0xc00
	ds_read_b64_tr_b16 v[66:67], v0 offset:0xa00
	ds_read_b64_tr_b16 v[68:69], v0 offset:0xe00
	s_add_i32 s18, s52, 0xffffe000
	s_mov_b32 s46, s66
	s_mov_b32 s47, s67
	buffer_load_dwordx4 v[170:173], v185, s[64:67], s18 offen
	buffer_load_dwordx4 v[174:177], v185, s[44:47], s18 offen
	s_and_saveexec_b64 s[18:19], s[42:43]
	s_cbranch_execz .LBB0_251
	s_add_i32 s28, s68, 0xfffff000
	buffer_load_dwordx4 v[158:161], v186, s[60:63], s28 offen
.LBB0_251:
	s_or_b64 exec, exec, s[18:19]
	s_waitcnt lgkmcnt(0)
	ds_read_b64_tr_b16 v[212:213], v0 offset:0x1000
	ds_read_b64_tr_b16 v[214:215], v0 offset:0x1400
	ds_read_b64_tr_b16 v[216:217], v0 offset:0x1200
	ds_read_b64_tr_b16 v[218:219], v0 offset:0x1600
	ds_read_b64_tr_b16 v[220:221], v0 offset:0x1800
	ds_read_b64_tr_b16 v[222:223], v0 offset:0x1c00
	ds_read_b64_tr_b16 v[228:229], v0 offset:0x1a00
	ds_read_b64_tr_b16 v[230:231], v0 offset:0x1e00
	s_nop 0
	v_mfma_f32_32x32x16_bf16 v[18:33], v[34:37], v[78:81], v[18:33]
	v_add_f32_e32 v238, v82, v195
	v_add_f32_e32 v239, v84, v196
	v_add_f32_e32 v240, v83, v85
	v_add_f32_e32 v241, v86, v87
	v_add_f32_e32 v238, v238, v239
	v_add_f32_e32 v240, v240, v241
	v_mfma_f32_32x32x16_bf16 v[2:17], v[34:37], v[74:77], v[2:17]
	v_max_f32_e32 v34, v114, v115
	v_max3_f32 v35, v116, v117, v99
	v_max3_f32 v34, v34, v98, v100
	v_max3_f32 v35, v35, v118, v119
	v_mfma_f32_32x32x16_bf16 v[18:33], v[42:45], v[70:73], v[18:33]
	v_max3_f32 v34, v34, v101, v120
	v_max3_f32 v35, v35, v102, v103
	v_add_f32_e32 v238, v240, v238
	v_add_f32_e32 v239, v88, v89
	v_add_f32_e32 v241, v90, v91
	v_mfma_f32_32x32x16_bf16 v[2:17], v[42:45], v[66:69], v[2:17]
	v_max3_f32 v34, v34, v121, v104
	v_max3_f32 v34, v34, v105, v124
	v_max3_f32 v35, v35, v122, v123
	v_add_f32_e32 v239, v239, v241
	v_add_f32_e32 v240, v92, v93
	v_add_f32_e32 v241, v94, v95
	s_waitcnt lgkmcnt(0)
	s_nop 0
	v_mfma_f32_32x32x16_bf16 v[18:33], v[46:49], v[212:215], v[18:33]
	v_max3_f32 v34, v34, v125, v108
	v_max3_f32 v35, v35, v106, v107
	v_add_f32_e32 v238, v239, v238
	v_add_f32_e32 v240, v240, v241
	s_waitcnt vmcnt(3)
	v_add_u32_e32 v67, s69, v187
	ds_write_b128 v67, v[162:165]
	v_mfma_f32_32x32x16_bf16 v[2:17], v[46:49], v[216:219], v[2:17]
	v_max3_f32 v34, v34, v109, v128
	v_max3_f32 v35, v35, v126, v127
	v_add_f32_e32 v238, v240, v238
	v_add_f32_e32 v239, v96, v97
	v_add_f32_e32 v241, v197, v198
	s_waitcnt vmcnt(2)
	ds_write_b128 v188, v[166:169] offset:24576
	v_mfma_f32_32x32x16_bf16 v[18:33], v[38:41], v[220:223], v[18:33]
	v_max3_f32 v34, v34, v129, v112
	v_max3_f32 v35, v35, v110, v111
	v_add_f32_e32 v239, v239, v241
	v_add_f32_e32 v240, v199, v200
	v_add_f32_e32 v241, v201, v202
	s_and_saveexec_b64 s[18:19], s[42:43]
	ds_write_b128 v193, v[154:157] offset:24704
	s_or_b64 exec, exec, s[18:19]
	v_add_f32_e32 v238, v239, v238
	v_add_f32_e32 v240, v240, v241
	v_mfma_f32_32x32x16_bf16 v[2:17], v[38:41], v[228:231], v[2:17]
	v_max3_f32 v34, v34, v113, v35
	v_cmp_lt_f32_e32 vcc, s35, v34
	v_add_f32_e32 v238, v240, v238
	v_add_f32_e32 v239, v203, v204
	v_add_f32_e32 v241, v205, v206
	v_add_f32_e32 v239, v239, v241
	v_add_f32_e32 v240, v207, v208
	v_add_f32_e32 v241, v209, v210
	v_add_f32_e32 v238, v239, v238
	v_add_f32_e32 v240, v240, v241
	v_add_f32_e32 v238, v240, v238
	v_add_f32_e32 v194, v194, v238
	s_cbranch_vccnz .LBB0_272
; #define SBAR() __builtin_amdgcn_sched_barrier(0)
; #define MF(A, B, C) __builtin_amdgcn_mfma_f32_32x32x16_bf16(A, B, C, 0, 0, 0)
; template <int KB, bool HASY>
; __device__ __forceinline__ void phaseA(f32x16& X0, f32x16& X1, f32x16& Y0, f32x16& Y1, bf16x8& pa0, bf16x8& pa1, bf16x8& pa2, bf16x8& pa3,
;                                        const bf16x8* qr, const f32x16& negm, int kaddr, VFr& vf, int vb, float& l_reg) {
;   SBAR();
;   float ls = 0.f;
;   bf16x8 k0 = rd128<KOFF(KB, 0, 0)>(kaddr), k1 = rd128<KOFF(KB, 1, 0)>(kaddr), k2 = rd128<KOFF(KB, 0, 1)>(kaddr), k3 = rd128<KOFF(KB, 1, 1)>(kaddr);
;   if (HASY) { EXP4(Y0, 0); EXP4(Y0, 4); }
;   SBAR(); WAIT4(k0, k1, k2, k3);
;   bf16x8 k4 = rd128<KOFF(KB, 0, 2)>(kaddr), k5 = rd128<KOFF(KB, 1, 2)>(kaddr), k6 = rd128<KOFF(KB, 0, 3)>(kaddr), k7 = rd128<KOFF(KB, 1, 3)>(kaddr);
;   SBAR();
;   X0 = MF(k0, qr[0], negm); if (HASY) { EXP4(Y0, 8); SUM4(Y0, 0); } SBAR();
;   X1 = MF(k1, qr[0], negm); if (HASY) { EXP4(Y0, 12); SUM4(Y0, 4); } SBAR();
;   X0 = MF(k2, qr[1], X0); if (HASY) { PACK8(Y0, 0, pa0); } SBAR();
;   X1 = MF(k3, qr[1], X1); if (HASY) { EXP4(Y1, 0); SUM4(Y0, 8); } SBAR();
;   WAIT4(k4, k5, k6, k7);
;   bf16x8 k8 = rd128<KOFF(KB, 0, 4)>(kaddr), k9 = rd128<KOFF(KB, 1, 4)>(kaddr), k10 = rd128<KOFF(KB, 0, 5)>(kaddr), k11 = rd128<KOFF(KB, 1, 5)>(kaddr);
;   SBAR();
;   X0 = MF(k4, qr[2], X0); if (HASY) { EXP4(Y1, 4); SUM4(Y0, 12); } SBAR();
;   X1 = MF(k5, qr[2], X1); if (HASY) { PACK8(Y0, 8, pa1); } SBAR();
;   X0 = MF(k6, qr[3], X0); if (HASY) { EXP4(Y1, 8); SUM4(Y1, 0); } SBAR();
;   X1 = MF(k7, qr[3], X1); if (HASY) { EXP4(Y1, 12); SUM4(Y1, 4); } SBAR();
;   WAIT4(k8, k9, k10, k11);
;   SBAR();
;   X0 = MF(k8, qr[4], X0); if (HASY) { PACK8(Y1, 0, pa2); } SBAR();
;   X1 = MF(k9, qr[4], X1); if (HASY) { SUM4(Y1, 8); SUM4(Y1, 12); } SBAR();
;   X0 = MF(k10, qr[5], X0); if (HASY) { PACK8(Y1, 8, pa3); } SBAR();
;   X1 = MF(k11, qr[5], X1); if (HASY) vfr_issue<0>(vf, vb);
; __device__ __forceinline__ void attn_unit(const bf16_t* __restrict__ Qb, const bf16_t* __restrict__ KNh, const bf16_t* __restrict__ KRb, const bf16_t* __restrict__ Vh,
;                                           bf16_t* __restrict__ Ob, int nkeys, char* lds, int tid_in) {
;     ...
;     phaseA<0, true>(pA0, pA1, pB0, pB1, pa0, pa1, pa2, pa3, qr, negm, kaddr, vf, vb0 + vprev, l_reg);
;     if (j + 3 < NT) SLOAD(SE, (j + 3) * KVBLK); SBAR();
.LBB0_259:
	v_add_u32_e32 v237, s76, v192
	s_waitcnt lgkmcnt(0)
	s_barrier
	ds_read_b128 v[66:69], v184 offset:0
	ds_read_b128 v[212:215], v184 offset:0x1a00
	ds_read_b128 v[216:219], v184 offset:32
	v_exp_f32_e32 v195, v114
	v_exp_f32_e32 v197, v115
	v_exp_f32_e32 v198, v116
	v_exp_f32_e32 v201, v117
	v_exp_f32_e32 v196, v118
	v_exp_f32_e32 v199, v119
	v_exp_f32_e32 v200, v120
	v_exp_f32_e32 v202, v121
	ds_read_b128 v[118:121], v184 offset:0x1a20
	ds_read_b128 v[220:223], v184 offset:64
	ds_read_b128 v[228:231], v184 offset:0x1a40
	ds_read_b128 v[238:241], v184 offset:0x60
	ds_read_b128 v[242:245], v184 offset:0x1a60
	s_waitcnt lgkmcnt(7)
	v_mfma_f32_32x32x16_bf16 v[82:97], v[66:69], v[150:153], v[50:65]
	v_exp_f32_e32 v203, v122
	v_exp_f32_e32 v204, v123
	v_exp_f32_e32 v205, v124
	v_exp_f32_e32 v206, v125
	s_waitcnt lgkmcnt(6)
	v_mfma_f32_32x32x16_bf16 v[66:81], v[212:215], v[150:153], v[50:65]
	v_exp_f32_e32 v207, v126
	v_exp_f32_e32 v208, v127
	v_exp_f32_e32 v209, v128
	v_exp_f32_e32 v210, v129
	s_waitcnt lgkmcnt(5)
	v_mfma_f32_32x32x16_bf16 v[82:97], v[216:219], v[146:149], v[82:97]
	v_cvt_pk_bf16_f32 v114, v195, v197
	v_cvt_pk_bf16_f32 v115, v198, v201
	v_cvt_pk_bf16_f32 v116, v196, v199
	v_cvt_pk_bf16_f32 v117, v200, v202
	s_waitcnt lgkmcnt(4)
	v_mfma_f32_32x32x16_bf16 v[66:81], v[118:121], v[146:149], v[66:81]
	v_exp_f32_e32 v211, v98
	v_exp_f32_e32 v212, v99
	v_exp_f32_e32 v213, v100
	v_exp_f32_e32 v214, v101
	ds_read_b128 v[98:101], v184 offset:0x80
	ds_read_b128 v[118:121], v184 offset:0x1a80
	ds_read_b128 v[122:125], v184 offset:0xa0
	ds_read_b128 v[246:249], v184 offset:0x1aa0
	s_waitcnt lgkmcnt(4)
	v_mfma_f32_32x32x16_bf16 v[82:97], v[220:223], v[142:145], v[82:97]
	v_exp_f32_e32 v215, v102
	v_exp_f32_e32 v216, v103
	v_exp_f32_e32 v217, v104
	v_exp_f32_e32 v218, v105
	v_mfma_f32_32x32x16_bf16 v[66:81], v[228:231], v[142:145], v[66:81]
	v_cvt_pk_bf16_f32 v102, v203, v204
	v_cvt_pk_bf16_f32 v103, v205, v206
	v_cvt_pk_bf16_f32 v104, v207, v208
	v_cvt_pk_bf16_f32 v105, v209, v210
	v_mfma_f32_32x32x16_bf16 v[82:97], v[238:241], v[138:141], v[82:97]
	v_exp_f32_e32 v219, v106
	v_exp_f32_e32 v220, v107
	v_exp_f32_e32 v221, v108
	v_exp_f32_e32 v222, v109
	v_mfma_f32_32x32x16_bf16 v[66:81], v[242:245], v[138:141], v[66:81]
	v_exp_f32_e32 v223, v110
	v_exp_f32_e32 v234, v111
	v_exp_f32_e32 v235, v112
	v_exp_f32_e32 v236, v113
	s_waitcnt lgkmcnt(0)
	s_nop 0
	v_mfma_f32_32x32x16_bf16 v[82:97], v[98:101], v[134:137], v[82:97]
	v_cvt_pk_bf16_f32 v106, v211, v212
	v_cvt_pk_bf16_f32 v107, v213, v214
	v_cvt_pk_bf16_f32 v108, v215, v216
	v_cvt_pk_bf16_f32 v109, v217, v218
	v_mfma_f32_32x32x16_bf16 v[66:81], v[118:121], v[134:137], v[66:81]
	v_mfma_f32_32x32x16_bf16 v[82:97], v[122:125], v[130:133], v[82:97]
	v_cvt_pk_bf16_f32 v98, v219, v220
	v_cvt_pk_bf16_f32 v99, v221, v222
	v_cvt_pk_bf16_f32 v100, v223, v234
	v_cvt_pk_bf16_f32 v101, v235, v236
	ds_read_b64_tr_b16 v[126:127], v237 offset:0
	ds_read_b64_tr_b16 v[128:129], v237 offset:0x400
	ds_read_b64_tr_b16 v[122:123], v237 offset:0x200
	v_mfma_f32_32x32x16_bf16 v[66:81], v[246:249], v[130:133], v[66:81]
	ds_read_b64_tr_b16 v[124:125], v237 offset:0x600
	ds_read_b64_tr_b16 v[118:119], v237 offset:0x800
	ds_read_b64_tr_b16 v[120:121], v237 offset:0xc00
	ds_read_b64_tr_b16 v[110:111], v237 offset:0xa00
	ds_read_b64_tr_b16 v[112:113], v237 offset:0xe00
	s_cmp_ge_u32 s39, s38
	s_cselect_b64 s[18:19], -1, 0
	s_and_b64 vcc, exec, s[18:19]
	s_cbranch_vccnz .LBB0_263
	s_mov_b32 s46, s66
	s_mov_b32 s47, s67
	buffer_load_dwordx4 v[162:165], v185, s[64:67], s52 offen
	buffer_load_dwordx4 v[166:169], v185, s[44:47], s52 offen
	s_and_saveexec_b64 s[28:29], s[42:43]
	s_cbranch_execz .LBB0_262
	buffer_load_dwordx4 v[154:157], v186, s[60:63], s68 offen

; #define SBAR() __builtin_amdgcn_sched_barrier(0)
; #define MX3(a, b, c) __builtin_fmaxf(__builtin_fmaxf((a), (b)), (c))
; #define MF(A, B, C) __builtin_amdgcn_mfma_f32_32x32x16_bf16(A, B, C, 0, 0, 0)
; #define VWAIT(f) asm volatile("s_waitcnt lgkmcnt(0)" : "+v"(f.a0), "+v"(f.b0), "+v"(f.c0), "+v"(f.d0), "+v"(f.a1), "+v"(f.b1), "+v"(f.c1), "+v"(f.d1) :: "memory")
; #define SWAIT() do { asm volatile("s_waitcnt vmcnt(3)" ::: "memory"); } while (0)
; template <bool HASX>
; __device__ __forceinline__ float phaseB(f32x16* o, bf16x8 pa0, bf16x8 pa1, bf16x8 pa2, bf16x8 pa3, VFr& f, int vb, const f32x16& X0, const f32x16& X1) {
;   SBAR(); VWAIT(f); VFr g; vfr_issue<2>(g, vb); SBAR();
;   float a = 0.f, b = 0.f;
;   o[0] = MF(pa0, PKV(f.a0, f.b0), o[0]); SBAR(); o[1] = MF(pa0, PKV(f.c0, f.d0), o[1]);
;   if (HASX) { a = MX3(X0[0], X0[1], X1[0]); b = MX3(X0[2], X0[3], X1[1]); a = MX3(a, X1[2], X1[3]); b = MX3(b, X0[4], X0[5]); } SBAR();
;   o[0] = MF(pa1, PKV(f.a1, f.b1), o[0]); if (HASX) { a = MX3(a, X0[6], X0[7]); b = MX3(b, X1[4], X1[5]); } SBAR();
;   o[1] = MF(pa1, PKV(f.c1, f.d1), o[1]); if (HASX) { a = MX3(a, X1[6], X1[7]); b = MX3(b, X0[8], X0[9]); a = MX3(a, X0[10], X0[11]); } SBAR();
;   VWAIT(g); SBAR();
;   o[0] = MF(pa2, PKV(g.a0, g.b0), o[0]); if (HASX) { b = MX3(b, X1[8], X1[9]); a = MX3(a, X1[10], X1[11]); } SBAR();
;   o[1] = MF(pa2, PKV(g.c0, g.d0), o[1]); if (HASX) { b = MX3(b, X0[12], X0[13]); a = MX3(a, X0[14], X0[15]); } SBAR();
;   o[0] = MF(pa3, PKV(g.a1, g.b1), o[0]); if (HASX) { b = MX3(b, X1[12], X1[13]); a = MX3(a, X1[14], X1[15]); } SBAR();
;   o[1] = MF(pa3, PKV(g.c1, g.d1), o[1]); SBAR();
;   float pmax = __builtin_fmaxf(a, b);
;   if (HASX) { auto rr = __builtin_amdgcn_permlane32_swap(__float_as_uint(pmax), __float_as_uint(pmax), false, false); pmax = __builtin_fmaxf(__uint_as_float(rr[0]), __uint_as_float(rr[1])); }
;   return pmax;
; }
; __device__ __forceinline__ void attn_unit(const bf16_t* __restrict__ Qb, const bf16_t* __restrict__ KNh, const bf16_t* __restrict__ KRb, const bf16_t* __restrict__ Vh,
;                                           bf16_t* __restrict__ Ob, int nkeys, char* lds, int tid_in) {
;     ...
;     alA = decide<false>(phaseB<true>(o, pa0, pa1, pa2, pa3, vf, vb0 + vprev, pA0, pA1), pA0, pA1, m_reg, negm);
;     SWAIT(); SWRITE(1, vnext, SO);
.LBB0_263:
	s_waitcnt lgkmcnt(0)
	ds_read_b64_tr_b16 v[228:229], v237 offset:0x1000
	ds_read_b64_tr_b16 v[230:231], v237 offset:0x1400
	ds_read_b64_tr_b16 v[238:239], v237 offset:0x1200
	ds_read_b64_tr_b16 v[240:241], v237 offset:0x1600
	ds_read_b64_tr_b16 v[242:243], v237 offset:0x1800
	ds_read_b64_tr_b16 v[244:245], v237 offset:0x1c00
	ds_read_b64_tr_b16 v[246:247], v237 offset:0x1a00
	ds_read_b64_tr_b16 v[248:249], v237 offset:0x1e00
	s_nop 0
	v_mfma_f32_32x32x16_bf16 v[18:33], v[114:117], v[126:129], v[18:33]
	v_add_f32_e32 v34, v195, v197
	v_add_f32_e32 v35, v198, v201
	v_add_f32_e32 v36, v196, v199
	v_add_f32_e32 v37, v200, v202
	v_add_f32_e32 v34, v34, v35
	v_add_f32_e32 v36, v36, v37
	v_mfma_f32_32x32x16_bf16 v[2:17], v[114:117], v[122:125], v[2:17]
	v_max_f32_e32 v114, v82, v83
	v_max3_f32 v115, v84, v85, v67
	v_max3_f32 v114, v114, v66, v68
	v_max3_f32 v115, v115, v86, v87
	v_mfma_f32_32x32x16_bf16 v[18:33], v[102:105], v[118:121], v[18:33]
	v_max3_f32 v114, v114, v69, v88
	v_max3_f32 v115, v115, v70, v71
	v_add_f32_e32 v34, v36, v34
	v_add_f32_e32 v35, v203, v204
	v_add_f32_e32 v37, v205, v206
	v_mfma_f32_32x32x16_bf16 v[2:17], v[102:105], v[110:113], v[2:17]
	v_max3_f32 v102, v114, v89, v72
	v_max3_f32 v103, v115, v90, v91
	v_max3_f32 v102, v102, v73, v92
	v_add_f32_e32 v35, v35, v37
	v_add_f32_e32 v36, v207, v208
	v_add_f32_e32 v37, v209, v210
	s_waitcnt lgkmcnt(0)
	s_nop 0
	v_mfma_f32_32x32x16_bf16 v[18:33], v[106:109], v[228:231], v[18:33]
	v_max3_f32 v103, v103, v74, v75
	v_max3_f32 v102, v102, v93, v76
	v_add_f32_e32 v34, v35, v34
	v_add_f32_e32 v36, v36, v37
	s_cmp_ge_u32 s39, s38
	s_cbranch_scc0 .Lmy_h1w
	s_waitcnt vmcnt(0)
.Lmy_h1w:
	s_waitcnt vmcnt(3)
	v_add_u32_e32 v110, s53, v187
	ds_write_b128 v110, v[170:173]
	v_mfma_f32_32x32x16_bf16 v[2:17], v[106:109], v[238:241], v[2:17]
	v_max3_f32 v103, v103, v94, v95
	v_max3_f32 v102, v102, v77, v96
	v_add_f32_e32 v34, v36, v34
	v_add_f32_e32 v35, v211, v212
	v_add_f32_e32 v37, v213, v214
	s_waitcnt vmcnt(2)
	ds_write_b128 v188, v[174:177] offset:37888
	v_mfma_f32_32x32x16_bf16 v[18:33], v[98:101], v[242:245], v[18:33]
	v_max3_f32 v103, v103, v78, v79
	v_max3_f32 v102, v102, v97, v80
	v_add_f32_e32 v35, v35, v37
	v_add_f32_e32 v36, v215, v216
	v_add_f32_e32 v37, v217, v218
	s_and_saveexec_b64 s[28:29], s[42:43]
	ds_write_b128 v193, v[158:161] offset:38016
	s_or_b64 exec, exec, s[28:29]
	v_add_f32_e32 v34, v35, v34
	v_add_f32_e32 v36, v36, v37
	v_mfma_f32_32x32x16_bf16 v[2:17], v[98:101], v[246:249], v[2:17]
	v_max3_f32 v98, v102, v81, v103
	v_cmp_lt_f32_e32 vcc, s35, v98
	v_add_f32_e32 v34, v36, v34
	v_add_f32_e32 v35, v219, v220
	v_add_f32_e32 v37, v221, v222
	v_add_f32_e32 v35, v35, v37
	v_add_f32_e32 v36, v223, v234
	v_add_f32_e32 v37, v235, v236
	v_add_f32_e32 v34, v35, v34
	v_add_f32_e32 v36, v36, v37
	v_add_f32_e32 v34, v36, v34
	v_add_f32_e32 v194, v34, v194
	s_cbranch_vccnz .LBB0_273

; template <bool HASX>
; __device__ __forceinline__ float phaseB(f32x16* o, bf16x8 pa0, bf16x8 pa1, bf16x8 pa2, bf16x8 pa3, VFr& f, int vb, const f32x16& X0, const f32x16& X1) {
;     ...
;   float pmax = __builtin_fmaxf(a, b);
;   if (HASX) { auto rr = __builtin_amdgcn_permlane32_swap(__float_as_uint(pmax), __float_as_uint(pmax), false, false); pmax = __builtin_fmaxf(__uint_as_float(rr[0]), __uint_as_float(rr[1])); }
; template <bool FIRST>
; __device__ __forceinline__ float decide(float pmax, f32x16& p0, f32x16& p1, float& m_reg, f32x16& negm) {
;   float alpha = 1.f;
;   if (FIRST || __builtin_expect(__any(pmax > THR2), 0)) {
;     const float dl = FIRST ? pmax : __builtin_fmaxf(pmax, 0.f); m_reg += dl;
; #pragma unroll
;     for (int r = 0; r < 16; ++r) { p0[r] -= dl; p1[r] -= dl; }
; #pragma unroll
;     for (int r = 0; r < 16; ++r) negm[r] = -m_reg;
;     if (!FIRST) alpha = __builtin_amdgcn_exp2f(-dl);
;   }
;   return alpha;
.LBB0_272:
	v_mov_b32_e32 v35, v34
	s_nop 1
	v_permlane32_swap_b32_e32 v34, v35
	v_max_f32_e32 v34, v34, v35
	v_max_f32_e32 v34, v34, v34
	v_max_f32_e32 v35, 0, v34
	v_exp_f32_e64 v66, -v35
	v_add_f32_e32 v189, v189, v35
	v_xor_b32_e32 v34, 0x80000000, v189
	v_sub_f32_e32 v129, v129, v35
	v_sub_f32_e32 v128, v128, v35
	v_sub_f32_e32 v127, v127, v35
	v_sub_f32_e32 v126, v126, v35
	v_sub_f32_e32 v125, v125, v35
	v_sub_f32_e32 v124, v124, v35
	v_sub_f32_e32 v123, v123, v35
	v_sub_f32_e32 v122, v122, v35
	v_sub_f32_e32 v121, v121, v35
	v_sub_f32_e32 v120, v120, v35
	v_sub_f32_e32 v119, v119, v35
	v_sub_f32_e32 v118, v118, v35
	v_sub_f32_e32 v117, v117, v35
	v_sub_f32_e32 v116, v116, v35
	v_sub_f32_e32 v115, v115, v35
	v_sub_f32_e32 v114, v114, v35
	v_sub_f32_e32 v113, v113, v35
	v_sub_f32_e32 v112, v112, v35
	v_sub_f32_e32 v111, v111, v35
	v_sub_f32_e32 v110, v110, v35
	v_sub_f32_e32 v109, v109, v35
	v_sub_f32_e32 v108, v108, v35
	v_sub_f32_e32 v107, v107, v35
	v_sub_f32_e32 v106, v106, v35
	v_sub_f32_e32 v105, v105, v35
	v_sub_f32_e32 v104, v104, v35
	v_sub_f32_e32 v103, v103, v35
	v_sub_f32_e32 v102, v102, v35
	v_sub_f32_e32 v101, v101, v35
	v_sub_f32_e32 v100, v100, v35
	v_sub_f32_e32 v99, v99, v35
	v_sub_f32_e32 v98, v98, v35
	v_mov_b32_e32 v35, v34
	v_mov_b32_e32 v36, v34
	v_mov_b32_e32 v37, v34
	v_mov_b32_e32 v38, v34
	v_mov_b32_e32 v39, v34
	v_mov_b32_e32 v40, v34
	v_mov_b32_e32 v41, v34
	v_mov_b32_e32 v42, v34
	v_mov_b32_e32 v43, v34
	v_mov_b32_e32 v44, v34
	v_mov_b32_e32 v45, v34
	v_mov_b32_e32 v46, v34
	v_mov_b32_e32 v47, v34
	v_mov_b32_e32 v48, v34
	v_mov_b32_e32 v49, v34
	v_mov_b32_e32 v50, v34
	v_mov_b32_e32 v51, v34
	v_mov_b32_e32 v52, v34
	v_mov_b32_e32 v53, v34
	v_mov_b32_e32 v54, v34
	v_mov_b32_e32 v55, v34
	v_mov_b32_e32 v56, v34
	v_mov_b32_e32 v57, v34
	v_mov_b32_e32 v58, v34
	v_mov_b32_e32 v59, v34
	v_mov_b32_e32 v60, v34
	v_mov_b32_e32 v61, v34
	v_mov_b32_e32 v62, v34
	v_mov_b32_e32 v63, v34
	v_mov_b32_e32 v64, v34
	v_mov_b32_e32 v65, v34
	s_branch .LBB0_253
.LBB0_273:
	v_mov_b32_e32 v99, v98
	s_nop 1
	v_permlane32_swap_b32_e32 v98, v99
	v_max_f32_e32 v99, v98, v99
	v_max_f32_e32 v34, v99, v99
	v_max_f32_e32 v35, 0, v34
	v_exp_f32_e64 v98, -v35
	v_add_f32_e32 v189, v189, v35
	v_xor_b32_e32 v34, 0x80000000, v189
	v_sub_f32_e32 v97, v97, v35
	v_sub_f32_e32 v96, v96, v35
	v_sub_f32_e32 v95, v95, v35
	v_sub_f32_e32 v94, v94, v35
	v_sub_f32_e32 v93, v93, v35
	v_sub_f32_e32 v92, v92, v35
	v_sub_f32_e32 v91, v91, v35
	v_sub_f32_e32 v90, v90, v35
	v_sub_f32_e32 v89, v89, v35
	v_sub_f32_e32 v88, v88, v35
	v_sub_f32_e32 v87, v87, v35
	v_sub_f32_e32 v86, v86, v35
	v_sub_f32_e32 v85, v85, v35
	v_sub_f32_e32 v84, v84, v35
	v_sub_f32_e32 v83, v83, v35
	v_sub_f32_e32 v82, v82, v35
	v_sub_f32_e32 v81, v81, v35
	v_sub_f32_e32 v80, v80, v35
	v_sub_f32_e32 v79, v79, v35
	v_sub_f32_e32 v78, v78, v35
	v_sub_f32_e32 v77, v77, v35
	v_sub_f32_e32 v76, v76, v35
	v_sub_f32_e32 v75, v75, v35
	v_sub_f32_e32 v74, v74, v35
	v_sub_f32_e32 v73, v73, v35
	v_sub_f32_e32 v72, v72, v35
	v_sub_f32_e32 v71, v71, v35
	v_sub_f32_e32 v70, v70, v35
	v_sub_f32_e32 v69, v69, v35
	v_sub_f32_e32 v68, v68, v35
	v_sub_f32_e32 v67, v67, v35
	v_sub_f32_e32 v66, v66, v35
	v_mov_b32_e32 v35, v34
	v_mov_b32_e32 v36, v34
	v_mov_b32_e32 v37, v34
	v_mov_b32_e32 v38, v34
	v_mov_b32_e32 v39, v34
	v_mov_b32_e32 v40, v34
	v_mov_b32_e32 v41, v34
	v_mov_b32_e32 v42, v34
	v_mov_b32_e32 v43, v34
	v_mov_b32_e32 v44, v34
	v_mov_b32_e32 v45, v34
	v_mov_b32_e32 v46, v34
	v_mov_b32_e32 v47, v34
	v_mov_b32_e32 v48, v34
	v_mov_b32_e32 v49, v34
	v_mov_b32_e32 v50, v34
	v_mov_b32_e32 v51, v34
	v_mov_b32_e32 v52, v34
	v_mov_b32_e32 v53, v34
	v_mov_b32_e32 v54, v34
	v_mov_b32_e32 v55, v34
	v_mov_b32_e32 v56, v34
	v_mov_b32_e32 v57, v34
	v_mov_b32_e32 v58, v34
	v_mov_b32_e32 v59, v34
	v_mov_b32_e32 v60, v34
	v_mov_b32_e32 v61, v34
	v_mov_b32_e32 v62, v34
	v_mov_b32_e32 v63, v34
	v_mov_b32_e32 v64, v34
	v_mov_b32_e32 v65, v34
	s_branch .LBB0_264
